# L1 in-proj rope epilogue: rope rows requested two groups ahead into dead fragment registers, counted vmcnt
# baseline (speedup 1.0000x reference)
; __device__ __forceinline__ unsigned cvt_pk_bf16(float lo, float hi) { unsigned r; asm volatile("v_cvt_pk_bf16_f32 %0, %1, %2" : "=v"(r) : "v"(lo), "v"(hi)); return r; }
;     __device__ __forceinline__ void operator()(const f32x4 (&acc)[2][2][4][2], const Unit& u, int wr, int wc, int fr, int fq) const {
;         const int b = u.pm / 33, tt = u.pm - b * 33; const bool dorope = (tt != 0) && (u.pn < 8); const float sc = (u.pn < 4) ? qscale : 1.0f;
;         const int rl = wr * 64 + fr, col0 = u.pn * BM + wc * 32 + 8 * fq, i0 = (wc & 1) * 16 + 4 * fq;
; #pragma unroll
;         for (int ai = 0; ai < 2; ++ai)
; #pragma unroll
;             for (int m = 0; m < 4; ++m) { const int r = rl + ai * HALF + m * 16; bf16_t* rowp = O + (size_t)(u.pm * BM + r) * ldc + col0;
;                 f32x4 t0 = (f32x4){1.f, 0.f, 1.f, 0.f}, t1 = t0;
;                 if (dorope) { const int pos = tt * 256 - 256 + r; const int pp = (i0 < 16) ? (pos >> 6) : (pos & 63); const f32x4* tb = (const f32x4*)(rope + (pp * 16 + (i0 & 15)) * 2); t0 = tb[0]; t1 = tb[1]; }
; #pragma unroll
;                 for (int bj = 0; bj < 2; ++bj) { const f32x4 v0 = acc[ai][bj][m][0], v1 = acc[ai][bj][m][1]; u32x4 w;
;                     w.x = cvt_pk_bf16((v0[0] * t0[0] - v0[1] * t0[1]) * sc, (v0[0] * t0[1] + v0[1] * t0[0]) * sc);
;                     w.y = cvt_pk_bf16((v0[2] * t0[2] - v0[3] * t0[3]) * sc, (v0[2] * t0[3] + v0[3] * t0[2]) * sc);
;                     w.z = cvt_pk_bf16((v1[0] * t1[0] - v1[1] * t1[1]) * sc, (v1[0] * t1[1] + v1[1] * t1[0]) * sc);
;                     w.w = cvt_pk_bf16((v1[2] * t1[2] - v1[3] * t1[3]) * sc, (v1[2] * t1[3] + v1[3] * t1[2]) * sc);
;                     *(u32x4*)(rowp + bj * HALF) = w; } }
.LBB0_1033:
	s_mul_hi_i32 s10, s64, 0x3e0f83e1
	s_lshr_b32 s11, s10, 31
	s_ashr_i32 s10, s10, 3
	s_add_i32 s10, s10, s11
	s_mul_i32 s10, s10, 33
	s_sub_i32 s33, s64, s10
	s_cmp_lg_u32 s33, 0
	s_cselect_b64 s[10:11], -1, 0
	s_cmp_lt_i32 s62, 8
	s_cselect_b64 s[66:67], -1, 0
	s_and_b64 s[66:67], s[10:11], s[66:67]
	s_lshl_b32 s33, s33, 8
	v_cndmask_b32_e64 v130, 0, 1, s[66:67]
	s_addk_i32 s33, 0xff00
	v_mov_b32_e32 v129, 0
	v_mov_b32_e32 v128, 1.0
	v_cmp_ne_u32_e64 s[10:11], 1, v130
	s_andn2_b64 vcc, exec, s[66:67]
	v_mov_b32_e32 v130, 1.0
	v_mov_b32_e32 v131, 0
	v_mov_b32_e32 v132, 1.0
	v_mov_b32_e32 v133, 0
	v_mov_b32_e32 v134, 1.0
	v_mov_b32_e32 v135, 0
	v_mov_b32_e32 v136, 1.0
	v_mov_b32_e32 v137, 0
	v_mov_b32_e32 v194, 1.0
	v_mov_b32_e32 v195, 0
	v_mov_b32_e32 v196, 1.0
	v_mov_b32_e32 v197, 0
	v_mov_b32_e32 v198, 1.0
	v_mov_b32_e32 v199, 0
	v_mov_b32_e32 v200, 1.0
	v_mov_b32_e32 v201, 0
	v_mov_b32_e32 v202, 1.0
	v_mov_b32_e32 v203, 0
	v_mov_b32_e32 v204, 1.0
	v_mov_b32_e32 v205, 0
	v_mov_b32_e32 v206, 1.0
	v_mov_b32_e32 v207, 0
	v_mov_b32_e32 v208, 1.0
	v_mov_b32_e32 v209, 0
	v_mov_b32_e32 v210, 1.0
	v_mov_b32_e32 v211, 0
	v_mov_b32_e32 v212, 1.0
	v_mov_b32_e32 v213, 0
	v_mov_b32_e32 v214, 1.0
	v_mov_b32_e32 v215, 0
	v_mov_b32_e32 v216, 1.0
	v_mov_b32_e32 v217, 0
	s_and_b64 vcc, exec, s[10:11]
	s_cbranch_vccnz .Lrope_skip_0
	v_add_u32_e32 v194, s33, v157
	v_ashrrev_i32_e32 v194, 6, v194
	v_cndmask_b32_e64 v194, v156, v194, s[6:7]
	v_lshl_or_b32 v194, v194, 5, v158
	v_ashrrev_i32_e32 v195, 31, v194
	v_lshl_add_u64 v[198:199], v[194:195], 2, s[50:51]
	global_load_dwordx4 v[194:197], v[198:199], off offset:16
	s_nop 0
	global_load_dwordx4 v[198:201], v[198:199], off
.Lrope_skip_0:
	s_and_b64 vcc, exec, s[10:11]
	s_cbranch_vccnz .Lrope_skip_1
	v_add_u32_e32 v206, s33, v163
	v_ashrrev_i32_e32 v206, 6, v206
	v_cndmask_b32_e64 v206, v160, v206, s[6:7]
	v_lshl_or_b32 v206, v206, 5, v158
	v_ashrrev_i32_e32 v207, 31, v206
	v_lshl_add_u64 v[206:207], v[206:207], 2, s[50:51]
	global_load_dwordx4 v[202:205], v[206:207], off offset:16
	s_nop 0
	global_load_dwordx4 v[206:209], v[206:207], off
.Lrope_skip_1:
.LBB0_1035:
	s_cmp_lt_i32 s62, 4
	s_cselect_b64 vcc, -1, 0
	s_lshl_b32 s55, s64, 8
	v_add_u32_e32 v189, s55, v157
	v_mov_b64_e32 v[190:191], s[44:45]
	s_waitcnt vmcnt(2)
	v_pk_mul_f32 v[192:193], v[124:125], v[198:199]
	v_mad_i64_i32 v[190:191], s[66:67], v189, s79, v[190:191]
	v_sub_f32_e32 v189, v192, v193
	v_pk_mul_f32 v[124:125], v[124:125], v[198:199] op_sel:[0,1] op_sel_hi:[1,0]
	v_pk_mul_f32 v[192:193], v[126:127], v[200:201]
	v_pk_mul_f32 v[126:127], v[126:127], v[200:201] op_sel:[0,1] op_sel_hi:[1,0]
	v_cndmask_b32_e32 v188, 1.0, v187, vcc
	s_and_b64 vcc, exec, s[10:11]
	s_cbranch_vccnz .Lrope_skip_2
	v_add_u32_e32 v210, s33, v164
	v_ashrrev_i32_e32 v210, 6, v210
	v_cndmask_b32_e64 v210, v161, v210, s[6:7]
	v_lshl_or_b32 v210, v210, 5, v158
	v_ashrrev_i32_e32 v211, 31, v210
	v_lshl_add_u64 v[214:215], v[210:211], 2, s[50:51]
	global_load_dwordx4 v[210:213], v[214:215], off offset:16
	s_nop 0
	global_load_dwordx4 v[214:217], v[214:215], off
.Lrope_skip_2:
	v_add_f32_e32 v124, v124, v125
	v_sub_f32_e32 v125, v192, v193
	v_add_f32_e32 v126, v126, v127
	v_mul_f32_e32 v124, v188, v124
	v_mul_f32_e32 v125, v188, v125
	v_mul_f32_e32 v126, v188, v126
	v_mul_f32_e32 v189, v188, v189
	v_cvt_pk_bf16_f32 v124, v189, v124
	v_cvt_pk_bf16_f32 v125, v125, v126
	v_pk_mul_f32 v[126:127], v[120:121], v[194:195]
	v_pk_mul_f32 v[120:121], v[120:121], v[194:195] op_sel:[0,1] op_sel_hi:[1,0]
	v_sub_f32_e32 v126, v126, v127
	v_add_f32_e32 v120, v120, v121
	v_mul_f32_e32 v126, v188, v126
	v_mul_f32_e32 v120, v188, v120
	v_cvt_pk_bf16_f32 v126, v126, v120
	v_pk_mul_f32 v[120:121], v[122:123], v[196:197]
	v_lshl_or_b32 v154, s62, 8, v170
	v_sub_f32_e32 v120, v120, v121
	v_mul_f32_e32 v127, v188, v120
	v_pk_mul_f32 v[120:121], v[122:123], v[196:197] op_sel:[0,1] op_sel_hi:[1,0]
	v_ashrrev_i32_e32 v155, 31, v154
	v_add_f32_e32 v120, v120, v121
	v_mul_f32_e32 v120, v188, v120
	v_cvt_pk_bf16_f32 v127, v127, v120
	v_pk_mul_f32 v[120:121], v[116:117], v[198:199]
	v_pk_mul_f32 v[116:117], v[116:117], v[198:199] op_sel:[0,1] op_sel_hi:[1,0]
	v_sub_f32_e32 v120, v120, v121
	v_add_f32_e32 v116, v116, v117
	v_lshl_add_u64 v[190:191], v[154:155], 1, v[190:191]
	v_mul_f32_e32 v120, v188, v120
	v_mul_f32_e32 v116, v188, v116
	global_store_dwordx4 v[190:191], v[124:127], off
	v_cvt_pk_bf16_f32 v116, v120, v116
	v_pk_mul_f32 v[120:121], v[118:119], v[200:201]
	v_pk_mul_f32 v[118:119], v[118:119], v[200:201] op_sel:[0,1] op_sel_hi:[1,0]
	v_sub_f32_e32 v117, v120, v121
	v_add_f32_e32 v118, v118, v119
	v_mul_f32_e32 v117, v188, v117
	v_mul_f32_e32 v118, v188, v118
	v_cvt_pk_bf16_f32 v117, v117, v118
	v_pk_mul_f32 v[118:119], v[112:113], v[194:195]
	v_pk_mul_f32 v[112:113], v[112:113], v[194:195] op_sel:[0,1] op_sel_hi:[1,0]
	v_sub_f32_e32 v118, v118, v119
	v_add_f32_e32 v112, v112, v113
	v_mul_f32_e32 v118, v188, v118
	v_mul_f32_e32 v112, v188, v112
	v_cvt_pk_bf16_f32 v118, v118, v112
	v_pk_mul_f32 v[112:113], v[114:115], v[196:197]
	s_and_b64 vcc, exec, s[10:11]
	v_sub_f32_e32 v112, v112, v113
	v_mul_f32_e32 v119, v188, v112
	v_pk_mul_f32 v[112:113], v[114:115], v[196:197] op_sel:[0,1] op_sel_hi:[1,0]
	v_mov_b32_e32 v130, 1.0
	v_add_f32_e32 v112, v112, v113
	v_mul_f32_e32 v112, v188, v112
	v_cvt_pk_bf16_f32 v119, v119, v112
	v_mov_b32_e32 v131, 0
	v_mov_b32_e32 v112, 1.0
	v_mov_b32_e32 v113, 0
	v_mov_b32_e32 v114, 1.0
	v_mov_b32_e32 v115, 0
	global_store_dwordx4 v[190:191], v[116:119], off offset:256
	s_nop 1
; __device__ __forceinline__ unsigned cvt_pk_bf16(float lo, float hi) { unsigned r; asm volatile("v_cvt_pk_bf16_f32 %0, %1, %2" : "=v"(r) : "v"(lo), "v"(hi)); return r; }
;     __device__ __forceinline__ void operator()(const f32x4 (&acc)[2][2][4][2], const Unit& u, int wr, int wc, int fr, int fq) const {
;     ...
;             for (int m = 0; m < 4; ++m) { const int r = rl + ai * HALF + m * 16; bf16_t* rowp = O + (size_t)(u.pm * BM + r) * ldc + col0;
;                 f32x4 t0 = (f32x4){1.f, 0.f, 1.f, 0.f}, t1 = t0;
;                 if (dorope) { const int pos = tt * 256 - 256 + r; const int pp = (i0 < 16) ? (pos >> 6) : (pos & 63); const f32x4* tb = (const f32x4*)(rope + (pp * 16 + (i0 & 15)) * 2); t0 = tb[0]; t1 = tb[1]; }
; #pragma unroll
;                 for (int bj = 0; bj < 2; ++bj) { const f32x4 v0 = acc[ai][bj][m][0], v1 = acc[ai][bj][m][1]; u32x4 w;
;                     w.x = cvt_pk_bf16((v0[0] * t0[0] - v0[1] * t0[1]) * sc, (v0[0] * t0[1] + v0[1] * t0[0]) * sc);
;                     w.y = cvt_pk_bf16((v0[2] * t0[2] - v0[3] * t0[3]) * sc, (v0[2] * t0[3] + v0[3] * t0[2]) * sc);
;                     w.z = cvt_pk_bf16((v1[0] * t1[0] - v1[1] * t1[1]) * sc, (v1[0] * t1[1] + v1[1] * t1[0]) * sc);
;                     w.w = cvt_pk_bf16((v1[2] * t1[2] - v1[3] * t1[3]) * sc, (v1[2] * t1[3] + v1[3] * t1[2]) * sc);
;                     *(u32x4*)(rowp + bj * HALF) = w; } }
.LBB0_1037:
	s_nop 0
	v_add_u32_e32 v118, s55, v163
	v_mov_b64_e32 v[116:117], s[44:45]
	v_mad_i64_i32 v[116:117], s[66:67], v118, s79, v[116:117]
	s_waitcnt vmcnt(4)
	s_and_b64 vcc, exec, s[10:11]
	s_cbranch_vccnz .Lrope_skip_3
	v_add_u32_e32 v198, s33, v165
	v_ashrrev_i32_e32 v198, 6, v198
	v_cndmask_b32_e64 v198, v162, v198, s[6:7]
	v_lshl_or_b32 v198, v198, 5, v158
	v_ashrrev_i32_e32 v199, 31, v198
	v_lshl_add_u64 v[198:199], v[198:199], 2, s[50:51]
	global_load_dwordx4 v[194:197], v[198:199], off offset:16
	s_nop 0
	global_load_dwordx4 v[198:201], v[198:199], off
.Lrope_skip_3:
	v_pk_mul_f32 v[118:119], v[108:109], v[206:207]
	v_pk_mul_f32 v[108:109], v[108:109], v[206:207] op_sel:[0,1] op_sel_hi:[1,0]
	v_sub_f32_e32 v118, v118, v119
	v_add_f32_e32 v108, v108, v109
	v_mul_f32_e32 v118, v188, v118
	v_mul_f32_e32 v108, v188, v108
	v_cvt_pk_bf16_f32 v108, v118, v108
	v_pk_mul_f32 v[118:119], v[110:111], v[208:209]
	v_pk_mul_f32 v[110:111], v[110:111], v[208:209] op_sel:[0,1] op_sel_hi:[1,0]
	v_sub_f32_e32 v109, v118, v119
	v_add_f32_e32 v110, v110, v111
	v_mul_f32_e32 v109, v188, v109
	v_mul_f32_e32 v110, v188, v110
	v_cvt_pk_bf16_f32 v109, v109, v110
	v_pk_mul_f32 v[110:111], v[104:105], v[202:203]
	v_pk_mul_f32 v[104:105], v[104:105], v[202:203] op_sel:[0,1] op_sel_hi:[1,0]
	v_sub_f32_e32 v110, v110, v111
	v_add_f32_e32 v104, v104, v105
	v_mul_f32_e32 v110, v188, v110
	v_mul_f32_e32 v104, v188, v104
	v_cvt_pk_bf16_f32 v110, v110, v104
	v_pk_mul_f32 v[104:105], v[106:107], v[204:205]
	v_lshl_add_u64 v[116:117], v[154:155], 1, v[116:117]
	v_sub_f32_e32 v104, v104, v105
	v_mul_f32_e32 v111, v188, v104
	v_pk_mul_f32 v[104:105], v[106:107], v[204:205] op_sel:[0,1] op_sel_hi:[1,0]
	s_and_b64 vcc, exec, s[10:11]
	v_add_f32_e32 v104, v104, v105
	v_mul_f32_e32 v104, v188, v104
	v_cvt_pk_bf16_f32 v111, v111, v104
	v_pk_mul_f32 v[104:105], v[100:101], v[206:207]
	v_pk_mul_f32 v[100:101], v[100:101], v[206:207] op_sel:[0,1] op_sel_hi:[1,0]
	v_sub_f32_e32 v104, v104, v105
	v_add_f32_e32 v100, v100, v101
	v_mul_f32_e32 v104, v188, v104
	v_mul_f32_e32 v100, v188, v100
	global_store_dwordx4 v[116:117], v[108:111], off
	v_cvt_pk_bf16_f32 v100, v104, v100
	v_pk_mul_f32 v[104:105], v[102:103], v[208:209]
	v_pk_mul_f32 v[102:103], v[102:103], v[208:209] op_sel:[0,1] op_sel_hi:[1,0]
	v_sub_f32_e32 v101, v104, v105
	v_add_f32_e32 v102, v102, v103
	v_mul_f32_e32 v101, v188, v101
	v_mul_f32_e32 v102, v188, v102
	v_cvt_pk_bf16_f32 v101, v101, v102
	v_pk_mul_f32 v[102:103], v[96:97], v[202:203]
	v_pk_mul_f32 v[96:97], v[96:97], v[202:203] op_sel:[0,1] op_sel_hi:[1,0]
	v_sub_f32_e32 v102, v102, v103
	v_add_f32_e32 v96, v96, v97
	v_mul_f32_e32 v102, v188, v102
	v_mul_f32_e32 v96, v188, v96
	v_cvt_pk_bf16_f32 v102, v102, v96
	v_pk_mul_f32 v[96:97], v[98:99], v[204:205]
	v_mov_b32_e32 v104, 1.0
	v_sub_f32_e32 v96, v96, v97
	v_mul_f32_e32 v103, v188, v96
	v_pk_mul_f32 v[96:97], v[98:99], v[204:205] op_sel:[0,1] op_sel_hi:[1,0]
	v_mov_b32_e32 v98, 1.0
	v_add_f32_e32 v96, v96, v97
	v_mul_f32_e32 v96, v188, v96
	v_cvt_pk_bf16_f32 v103, v103, v96
	global_store_dwordx4 v[116:117], v[100:103], off offset:256
	v_mov_b32_e32 v97, 0
	v_mov_b32_e32 v96, 1.0
	v_mov_b32_e32 v99, 0
	v_mov_b32_e32 v100, 1.0
	v_mov_b32_e32 v101, 0
	v_mov_b32_e32 v102, 1.0
	v_mov_b32_e32 v103, 0
	v_mov_b32_e32 v105, 0
	s_nop 1
.LBB0_1039:
	v_add_u32_e32 v108, s55, v164
	v_mov_b64_e32 v[106:107], s[44:45]
	v_mad_i64_i32 v[106:107], s[66:67], v108, s79, v[106:107]
	s_waitcnt vmcnt(6)
	s_and_b64 vcc, exec, s[10:11]
	s_cbranch_vccnz .Lrope_skip_4
	v_add_u32_e32 v202, s33, v166
	v_ashrrev_i32_e32 v202, 6, v202
	v_cndmask_b32_e64 v202, v156, v202, s[6:7]
	v_lshl_or_b32 v202, v202, 5, v158
	v_ashrrev_i32_e32 v203, 31, v202
	v_lshl_add_u64 v[206:207], v[202:203], 2, s[50:51]
	global_load_dwordx4 v[202:205], v[206:207], off offset:16
	s_nop 0
	global_load_dwordx4 v[206:209], v[206:207], off
.Lrope_skip_4:
	v_pk_mul_f32 v[108:109], v[92:93], v[214:215]
	v_pk_mul_f32 v[92:93], v[92:93], v[214:215] op_sel:[0,1] op_sel_hi:[1,0]
	v_sub_f32_e32 v108, v108, v109
	v_add_f32_e32 v92, v92, v93
	v_mul_f32_e32 v108, v188, v108
	v_mul_f32_e32 v92, v188, v92
	v_cvt_pk_bf16_f32 v92, v108, v92
	v_pk_mul_f32 v[108:109], v[94:95], v[216:217]
	v_pk_mul_f32 v[94:95], v[94:95], v[216:217] op_sel:[0,1] op_sel_hi:[1,0]
	v_sub_f32_e32 v93, v108, v109
	v_add_f32_e32 v94, v94, v95
	v_mul_f32_e32 v93, v188, v93
	v_mul_f32_e32 v94, v188, v94
	v_cvt_pk_bf16_f32 v93, v93, v94
	v_pk_mul_f32 v[94:95], v[88:89], v[210:211]
	v_pk_mul_f32 v[88:89], v[88:89], v[210:211] op_sel:[0,1] op_sel_hi:[1,0]
	v_sub_f32_e32 v94, v94, v95
	v_add_f32_e32 v88, v88, v89
	v_mul_f32_e32 v94, v188, v94
	v_mul_f32_e32 v88, v188, v88
	v_cvt_pk_bf16_f32 v94, v94, v88
	v_pk_mul_f32 v[88:89], v[90:91], v[212:213]
	v_lshl_add_u64 v[106:107], v[154:155], 1, v[106:107]
	v_sub_f32_e32 v88, v88, v89
	v_mul_f32_e32 v95, v188, v88
	v_pk_mul_f32 v[88:89], v[90:91], v[212:213] op_sel:[0,1] op_sel_hi:[1,0]
	s_and_b64 vcc, exec, s[10:11]
	v_add_f32_e32 v88, v88, v89
	v_mul_f32_e32 v88, v188, v88
	v_cvt_pk_bf16_f32 v95, v95, v88
	v_pk_mul_f32 v[88:89], v[84:85], v[214:215]
	v_pk_mul_f32 v[84:85], v[84:85], v[214:215] op_sel:[0,1] op_sel_hi:[1,0]
	v_sub_f32_e32 v88, v88, v89
	v_add_f32_e32 v84, v84, v85
	v_mul_f32_e32 v88, v188, v88
	v_mul_f32_e32 v84, v188, v84
	global_store_dwordx4 v[106:107], v[92:95], off
	v_cvt_pk_bf16_f32 v84, v88, v84
	v_pk_mul_f32 v[88:89], v[86:87], v[216:217]
	v_pk_mul_f32 v[86:87], v[86:87], v[216:217] op_sel:[0,1] op_sel_hi:[1,0]
	v_sub_f32_e32 v85, v88, v89
	v_add_f32_e32 v86, v86, v87
	v_mul_f32_e32 v85, v188, v85
	v_mul_f32_e32 v86, v188, v86
	v_cvt_pk_bf16_f32 v85, v85, v86
	v_pk_mul_f32 v[86:87], v[80:81], v[210:211]
	v_pk_mul_f32 v[80:81], v[80:81], v[210:211] op_sel:[0,1] op_sel_hi:[1,0]
	v_sub_f32_e32 v86, v86, v87
	v_add_f32_e32 v80, v80, v81
	v_mul_f32_e32 v86, v188, v86
	v_mul_f32_e32 v80, v188, v80
	v_cvt_pk_bf16_f32 v86, v86, v80
	v_pk_mul_f32 v[80:81], v[82:83], v[212:213]
	v_mov_b32_e32 v98, 1.0
	v_sub_f32_e32 v80, v80, v81
	v_mul_f32_e32 v87, v188, v80
	v_pk_mul_f32 v[80:81], v[82:83], v[212:213] op_sel:[0,1] op_sel_hi:[1,0]
	v_mov_b32_e32 v99, 0
	v_add_f32_e32 v80, v80, v81
	v_mul_f32_e32 v80, v188, v80
	v_cvt_pk_bf16_f32 v87, v87, v80
	v_mov_b32_e32 v80, 1.0
	v_mov_b32_e32 v81, 0
	v_mov_b32_e32 v82, 1.0
	v_mov_b32_e32 v83, 0
	global_store_dwordx4 v[106:107], v[84:87], off offset:256
	s_nop 1
; __device__ __forceinline__ unsigned cvt_pk_bf16(float lo, float hi) { unsigned r; asm volatile("v_cvt_pk_bf16_f32 %0, %1, %2" : "=v"(r) : "v"(lo), "v"(hi)); return r; }
;     __device__ __forceinline__ void operator()(const f32x4 (&acc)[2][2][4][2], const Unit& u, int wr, int wc, int fr, int fq) const {
;     ...
;             for (int m = 0; m < 4; ++m) { const int r = rl + ai * HALF + m * 16; bf16_t* rowp = O + (size_t)(u.pm * BM + r) * ldc + col0;
;                 f32x4 t0 = (f32x4){1.f, 0.f, 1.f, 0.f}, t1 = t0;
;                 if (dorope) { const int pos = tt * 256 - 256 + r; const int pp = (i0 < 16) ? (pos >> 6) : (pos & 63); const f32x4* tb = (const f32x4*)(rope + (pp * 16 + (i0 & 15)) * 2); t0 = tb[0]; t1 = tb[1]; }
; #pragma unroll
;                 for (int bj = 0; bj < 2; ++bj) { const f32x4 v0 = acc[ai][bj][m][0], v1 = acc[ai][bj][m][1]; u32x4 w;
;                     w.x = cvt_pk_bf16((v0[0] * t0[0] - v0[1] * t0[1]) * sc, (v0[0] * t0[1] + v0[1] * t0[0]) * sc);
;                     w.y = cvt_pk_bf16((v0[2] * t0[2] - v0[3] * t0[3]) * sc, (v0[2] * t0[3] + v0[3] * t0[2]) * sc);
;                     w.z = cvt_pk_bf16((v1[0] * t1[0] - v1[1] * t1[1]) * sc, (v1[0] * t1[1] + v1[1] * t1[0]) * sc);
;                     w.w = cvt_pk_bf16((v1[2] * t1[2] - v1[3] * t1[3]) * sc, (v1[2] * t1[3] + v1[3] * t1[2]) * sc);
;                     *(u32x4*)(rowp + bj * HALF) = w; } }
.LBB0_1041:
	s_nop 0
	v_add_u32_e32 v86, s55, v165
	v_mov_b64_e32 v[84:85], s[44:45]
	v_mad_i64_i32 v[84:85], s[66:67], v86, s79, v[84:85]
	s_waitcnt vmcnt(6)
	s_and_b64 vcc, exec, s[10:11]
	s_cbranch_vccnz .Lrope_skip_5
	v_add_u32_e32 v214, s33, v167
	v_ashrrev_i32_e32 v214, 6, v214
	v_cndmask_b32_e64 v214, v160, v214, s[6:7]
	v_lshl_or_b32 v214, v214, 5, v158
	v_ashrrev_i32_e32 v215, 31, v214
	v_lshl_add_u64 v[214:215], v[214:215], 2, s[50:51]
	global_load_dwordx4 v[210:213], v[214:215], off offset:16
	s_nop 0
	global_load_dwordx4 v[214:217], v[214:215], off
.Lrope_skip_5:
	v_pk_mul_f32 v[86:87], v[76:77], v[198:199]
	v_pk_mul_f32 v[76:77], v[76:77], v[198:199] op_sel:[0,1] op_sel_hi:[1,0]
	v_sub_f32_e32 v86, v86, v87
	v_add_f32_e32 v76, v76, v77
	v_mul_f32_e32 v86, v188, v86
	v_mul_f32_e32 v76, v188, v76
	v_cvt_pk_bf16_f32 v76, v86, v76
	v_pk_mul_f32 v[86:87], v[78:79], v[200:201]
	v_pk_mul_f32 v[78:79], v[78:79], v[200:201] op_sel:[0,1] op_sel_hi:[1,0]
	v_sub_f32_e32 v77, v86, v87
	v_add_f32_e32 v78, v78, v79
	v_mul_f32_e32 v77, v188, v77
	v_mul_f32_e32 v78, v188, v78
	v_cvt_pk_bf16_f32 v77, v77, v78
	v_pk_mul_f32 v[78:79], v[72:73], v[194:195]
	v_pk_mul_f32 v[72:73], v[72:73], v[194:195] op_sel:[0,1] op_sel_hi:[1,0]
	v_sub_f32_e32 v78, v78, v79
	v_add_f32_e32 v72, v72, v73
	v_mul_f32_e32 v78, v188, v78
	v_mul_f32_e32 v72, v188, v72
	v_cvt_pk_bf16_f32 v78, v78, v72
	v_pk_mul_f32 v[72:73], v[74:75], v[196:197]
	v_lshl_add_u64 v[84:85], v[154:155], 1, v[84:85]
	v_sub_f32_e32 v72, v72, v73
	v_mul_f32_e32 v79, v188, v72
	v_pk_mul_f32 v[72:73], v[74:75], v[196:197] op_sel:[0,1] op_sel_hi:[1,0]
	s_and_b64 vcc, exec, s[10:11]
	v_add_f32_e32 v72, v72, v73
	v_mul_f32_e32 v72, v188, v72
	v_cvt_pk_bf16_f32 v79, v79, v72
	v_pk_mul_f32 v[72:73], v[68:69], v[198:199]
	v_pk_mul_f32 v[68:69], v[68:69], v[198:199] op_sel:[0,1] op_sel_hi:[1,0]
	v_sub_f32_e32 v72, v72, v73
	v_add_f32_e32 v68, v68, v69
	v_mul_f32_e32 v72, v188, v72
	v_mul_f32_e32 v68, v188, v68
	global_store_dwordx4 v[84:85], v[76:79], off
	v_cvt_pk_bf16_f32 v68, v72, v68
	v_pk_mul_f32 v[72:73], v[70:71], v[200:201]
	v_pk_mul_f32 v[70:71], v[70:71], v[200:201] op_sel:[0,1] op_sel_hi:[1,0]
	v_sub_f32_e32 v69, v72, v73
	v_add_f32_e32 v70, v70, v71
	v_mul_f32_e32 v69, v188, v69
	v_mul_f32_e32 v70, v188, v70
	v_cvt_pk_bf16_f32 v69, v69, v70
	v_pk_mul_f32 v[70:71], v[64:65], v[194:195]
	v_pk_mul_f32 v[64:65], v[64:65], v[194:195] op_sel:[0,1] op_sel_hi:[1,0]
	v_sub_f32_e32 v70, v70, v71
	v_add_f32_e32 v64, v64, v65
	v_mul_f32_e32 v70, v188, v70
	v_mul_f32_e32 v64, v188, v64
	v_cvt_pk_bf16_f32 v70, v70, v64
	v_pk_mul_f32 v[64:65], v[66:67], v[196:197]
	v_mov_b32_e32 v72, 1.0
	v_sub_f32_e32 v64, v64, v65
	v_mul_f32_e32 v71, v188, v64
	v_pk_mul_f32 v[64:65], v[66:67], v[196:197] op_sel:[0,1] op_sel_hi:[1,0]
	v_mov_b32_e32 v66, 1.0
	v_add_f32_e32 v64, v64, v65
	v_mul_f32_e32 v64, v188, v64
	v_cvt_pk_bf16_f32 v71, v71, v64
	global_store_dwordx4 v[84:85], v[68:71], off offset:256
	v_mov_b32_e32 v65, 0
	v_mov_b32_e32 v64, 1.0
	v_mov_b32_e32 v67, 0
	v_mov_b32_e32 v68, 1.0
	v_mov_b32_e32 v69, 0
	v_mov_b32_e32 v70, 1.0
	v_mov_b32_e32 v71, 0
	v_mov_b32_e32 v73, 0
	s_nop 1
.LBB0_1043:
	v_add_u32_e32 v76, s55, v166
	v_mov_b64_e32 v[74:75], s[44:45]
	v_mad_i64_i32 v[74:75], s[66:67], v76, s79, v[74:75]
	s_waitcnt vmcnt(6)
	s_and_b64 vcc, exec, s[10:11]
	s_cbranch_vccnz .Lrope_skip_6
	v_add_u32_e32 v194, s33, v168
	v_ashrrev_i32_e32 v194, 6, v194
	v_cndmask_b32_e64 v194, v161, v194, s[6:7]
	v_lshl_or_b32 v194, v194, 5, v158
	v_ashrrev_i32_e32 v195, 31, v194
	v_lshl_add_u64 v[198:199], v[194:195], 2, s[50:51]
	global_load_dwordx4 v[194:197], v[198:199], off offset:16
	s_nop 0
	global_load_dwordx4 v[198:201], v[198:199], off
.Lrope_skip_6:
	v_pk_mul_f32 v[76:77], v[60:61], v[206:207]
	v_pk_mul_f32 v[60:61], v[60:61], v[206:207] op_sel:[0,1] op_sel_hi:[1,0]
	v_sub_f32_e32 v76, v76, v77
	v_add_f32_e32 v60, v60, v61
	v_mul_f32_e32 v76, v188, v76
	v_mul_f32_e32 v60, v188, v60
	v_cvt_pk_bf16_f32 v60, v76, v60
	v_pk_mul_f32 v[76:77], v[62:63], v[208:209]
	v_pk_mul_f32 v[62:63], v[62:63], v[208:209] op_sel:[0,1] op_sel_hi:[1,0]
	v_sub_f32_e32 v61, v76, v77
	v_add_f32_e32 v62, v62, v63
	v_mul_f32_e32 v61, v188, v61
	v_mul_f32_e32 v62, v188, v62
	v_cvt_pk_bf16_f32 v61, v61, v62
	v_pk_mul_f32 v[62:63], v[56:57], v[202:203]
	v_pk_mul_f32 v[56:57], v[56:57], v[202:203] op_sel:[0,1] op_sel_hi:[1,0]
	v_sub_f32_e32 v62, v62, v63
	v_add_f32_e32 v56, v56, v57
	v_mul_f32_e32 v62, v188, v62
	v_mul_f32_e32 v56, v188, v56
	v_cvt_pk_bf16_f32 v62, v62, v56
	v_pk_mul_f32 v[56:57], v[58:59], v[204:205]
	v_lshl_add_u64 v[74:75], v[154:155], 1, v[74:75]
	v_sub_f32_e32 v56, v56, v57
	v_mul_f32_e32 v63, v188, v56
	v_pk_mul_f32 v[56:57], v[58:59], v[204:205] op_sel:[0,1] op_sel_hi:[1,0]
	s_and_b64 vcc, exec, s[10:11]
	v_add_f32_e32 v56, v56, v57
	v_mul_f32_e32 v56, v188, v56
	v_cvt_pk_bf16_f32 v63, v63, v56
	v_pk_mul_f32 v[56:57], v[52:53], v[206:207]
	v_pk_mul_f32 v[52:53], v[52:53], v[206:207] op_sel:[0,1] op_sel_hi:[1,0]
	v_sub_f32_e32 v56, v56, v57
	v_add_f32_e32 v52, v52, v53
	v_mul_f32_e32 v56, v188, v56
	v_mul_f32_e32 v52, v188, v52
	global_store_dwordx4 v[74:75], v[60:63], off
	v_cvt_pk_bf16_f32 v52, v56, v52
	v_pk_mul_f32 v[56:57], v[54:55], v[208:209]
	v_pk_mul_f32 v[54:55], v[54:55], v[208:209] op_sel:[0,1] op_sel_hi:[1,0]
	v_sub_f32_e32 v53, v56, v57
	v_add_f32_e32 v54, v54, v55
	v_mul_f32_e32 v53, v188, v53
	v_mul_f32_e32 v54, v188, v54
	v_cvt_pk_bf16_f32 v53, v53, v54
	v_pk_mul_f32 v[54:55], v[48:49], v[202:203]
	v_pk_mul_f32 v[48:49], v[48:49], v[202:203] op_sel:[0,1] op_sel_hi:[1,0]
	v_sub_f32_e32 v54, v54, v55
	v_add_f32_e32 v48, v48, v49
	v_mul_f32_e32 v54, v188, v54
	v_mul_f32_e32 v48, v188, v48
	v_cvt_pk_bf16_f32 v54, v54, v48
	v_pk_mul_f32 v[48:49], v[50:51], v[204:205]
	v_mov_b32_e32 v66, 1.0
	v_sub_f32_e32 v48, v48, v49
	v_mul_f32_e32 v55, v188, v48
	v_pk_mul_f32 v[48:49], v[50:51], v[204:205] op_sel:[0,1] op_sel_hi:[1,0]
	v_mov_b32_e32 v67, 0
	v_add_f32_e32 v48, v48, v49
	v_mul_f32_e32 v48, v188, v48
	v_cvt_pk_bf16_f32 v55, v55, v48
	v_mov_b32_e32 v48, 1.0
	v_mov_b32_e32 v49, 0
	v_mov_b32_e32 v50, 1.0
	v_mov_b32_e32 v51, 0
	global_store_dwordx4 v[74:75], v[52:55], off offset:256
	s_nop 1
; __device__ __forceinline__ unsigned cvt_pk_bf16(float lo, float hi) { unsigned r; asm volatile("v_cvt_pk_bf16_f32 %0, %1, %2" : "=v"(r) : "v"(lo), "v"(hi)); return r; }
;     __device__ __forceinline__ void operator()(const f32x4 (&acc)[2][2][4][2], const Unit& u, int wr, int wc, int fr, int fq) const {
;     ...
;             for (int m = 0; m < 4; ++m) { const int r = rl + ai * HALF + m * 16; bf16_t* rowp = O + (size_t)(u.pm * BM + r) * ldc + col0;
;                 f32x4 t0 = (f32x4){1.f, 0.f, 1.f, 0.f}, t1 = t0;
;                 if (dorope) { const int pos = tt * 256 - 256 + r; const int pp = (i0 < 16) ? (pos >> 6) : (pos & 63); const f32x4* tb = (const f32x4*)(rope + (pp * 16 + (i0 & 15)) * 2); t0 = tb[0]; t1 = tb[1]; }
; #pragma unroll
;                 for (int bj = 0; bj < 2; ++bj) { const f32x4 v0 = acc[ai][bj][m][0], v1 = acc[ai][bj][m][1]; u32x4 w;
;                     w.x = cvt_pk_bf16((v0[0] * t0[0] - v0[1] * t0[1]) * sc, (v0[0] * t0[1] + v0[1] * t0[0]) * sc);
;                     w.y = cvt_pk_bf16((v0[2] * t0[2] - v0[3] * t0[3]) * sc, (v0[2] * t0[3] + v0[3] * t0[2]) * sc);
;                     w.z = cvt_pk_bf16((v1[0] * t1[0] - v1[1] * t1[1]) * sc, (v1[0] * t1[1] + v1[1] * t1[0]) * sc);
;                     w.w = cvt_pk_bf16((v1[2] * t1[2] - v1[3] * t1[3]) * sc, (v1[2] * t1[3] + v1[3] * t1[2]) * sc);
;                     *(u32x4*)(rowp + bj * HALF) = w; } }
.LBB0_1045:
	s_nop 0
	v_add_u32_e32 v54, s55, v167
	v_mov_b64_e32 v[52:53], s[44:45]
	v_mad_i64_i32 v[52:53], s[66:67], v54, s79, v[52:53]
	s_waitcnt vmcnt(6)
	s_and_b64 vcc, exec, s[10:11]
	s_cbranch_vccnz .Lrope_skip_7
	v_add_u32_e32 v206, s33, v169
	v_ashrrev_i32_e32 v206, 6, v206
	v_cndmask_b32_e64 v206, v162, v206, s[6:7]
	v_lshl_or_b32 v206, v206, 5, v158
	v_ashrrev_i32_e32 v207, 31, v206
	v_lshl_add_u64 v[206:207], v[206:207], 2, s[50:51]
	global_load_dwordx4 v[202:205], v[206:207], off offset:16
	s_nop 0
	global_load_dwordx4 v[206:209], v[206:207], off
.Lrope_skip_7:
	v_pk_mul_f32 v[54:55], v[44:45], v[214:215]
	v_pk_mul_f32 v[44:45], v[44:45], v[214:215] op_sel:[0,1] op_sel_hi:[1,0]
	v_sub_f32_e32 v54, v54, v55
	v_add_f32_e32 v44, v44, v45
	v_mul_f32_e32 v54, v188, v54
	v_mul_f32_e32 v44, v188, v44
	v_cvt_pk_bf16_f32 v44, v54, v44
	v_pk_mul_f32 v[54:55], v[46:47], v[216:217]
	v_pk_mul_f32 v[46:47], v[46:47], v[216:217] op_sel:[0,1] op_sel_hi:[1,0]
	v_sub_f32_e32 v45, v54, v55
	v_add_f32_e32 v46, v46, v47
	v_mul_f32_e32 v45, v188, v45
	v_mul_f32_e32 v46, v188, v46
	v_cvt_pk_bf16_f32 v45, v45, v46
	v_pk_mul_f32 v[46:47], v[40:41], v[210:211]
	v_pk_mul_f32 v[40:41], v[40:41], v[210:211] op_sel:[0,1] op_sel_hi:[1,0]
	v_sub_f32_e32 v46, v46, v47
	v_add_f32_e32 v40, v40, v41
	v_mul_f32_e32 v46, v188, v46
	v_mul_f32_e32 v40, v188, v40
	v_cvt_pk_bf16_f32 v46, v46, v40
	v_pk_mul_f32 v[40:41], v[42:43], v[212:213]
	v_lshl_add_u64 v[52:53], v[154:155], 1, v[52:53]
	v_sub_f32_e32 v40, v40, v41
	v_mul_f32_e32 v47, v188, v40
	v_pk_mul_f32 v[40:41], v[42:43], v[212:213] op_sel:[0,1] op_sel_hi:[1,0]
	s_and_b64 vcc, exec, s[10:11]
	v_add_f32_e32 v40, v40, v41
	v_mul_f32_e32 v40, v188, v40
	v_cvt_pk_bf16_f32 v47, v47, v40
	v_pk_mul_f32 v[40:41], v[36:37], v[214:215]
	v_pk_mul_f32 v[36:37], v[36:37], v[214:215] op_sel:[0,1] op_sel_hi:[1,0]
	v_sub_f32_e32 v40, v40, v41
	v_add_f32_e32 v36, v36, v37
	v_mul_f32_e32 v40, v188, v40
	v_mul_f32_e32 v36, v188, v36
	global_store_dwordx4 v[52:53], v[44:47], off
	v_cvt_pk_bf16_f32 v36, v40, v36
	v_pk_mul_f32 v[40:41], v[38:39], v[216:217]
	v_pk_mul_f32 v[38:39], v[38:39], v[216:217] op_sel:[0,1] op_sel_hi:[1,0]
	v_sub_f32_e32 v37, v40, v41
	v_add_f32_e32 v38, v38, v39
	v_mul_f32_e32 v37, v188, v37
	v_mul_f32_e32 v38, v188, v38
	v_cvt_pk_bf16_f32 v37, v37, v38
	v_pk_mul_f32 v[38:39], v[32:33], v[210:211]
	v_pk_mul_f32 v[32:33], v[32:33], v[210:211] op_sel:[0,1] op_sel_hi:[1,0]
	v_sub_f32_e32 v38, v38, v39
	v_add_f32_e32 v32, v32, v33
	v_mul_f32_e32 v38, v188, v38
	v_mul_f32_e32 v32, v188, v32
	v_cvt_pk_bf16_f32 v38, v38, v32
	v_pk_mul_f32 v[32:33], v[34:35], v[212:213]
	v_mov_b32_e32 v40, 1.0
	v_sub_f32_e32 v32, v32, v33
	v_mul_f32_e32 v39, v188, v32
	v_pk_mul_f32 v[32:33], v[34:35], v[212:213] op_sel:[0,1] op_sel_hi:[1,0]
	v_mov_b32_e32 v34, 1.0
	v_add_f32_e32 v32, v32, v33
	v_mul_f32_e32 v32, v188, v32
	v_cvt_pk_bf16_f32 v39, v39, v32
	global_store_dwordx4 v[52:53], v[36:39], off offset:256
	v_mov_b32_e32 v33, 0
	v_mov_b32_e32 v32, 1.0
	v_mov_b32_e32 v35, 0
	v_mov_b32_e32 v36, 1.0
	v_mov_b32_e32 v37, 0
	v_mov_b32_e32 v38, 1.0
	v_mov_b32_e32 v39, 0
	v_mov_b32_e32 v41, 0
	s_nop 1
; __device__ __forceinline__ unsigned cvt_pk_bf16(float lo, float hi) { unsigned r; asm volatile("v_cvt_pk_bf16_f32 %0, %1, %2" : "=v"(r) : "v"(lo), "v"(hi)); return r; }
;     __device__ __forceinline__ void operator()(const f32x4 (&acc)[2][2][4][2], const Unit& u, int wr, int wc, int fr, int fq) const {
;     ...
;             for (int m = 0; m < 4; ++m) { const int r = rl + ai * HALF + m * 16; bf16_t* rowp = O + (size_t)(u.pm * BM + r) * ldc + col0;
;                 f32x4 t0 = (f32x4){1.f, 0.f, 1.f, 0.f}, t1 = t0;
;                 if (dorope) { const int pos = tt * 256 - 256 + r; const int pp = (i0 < 16) ? (pos >> 6) : (pos & 63); const f32x4* tb = (const f32x4*)(rope + (pp * 16 + (i0 & 15)) * 2); t0 = tb[0]; t1 = tb[1]; }
; #pragma unroll
;                 for (int bj = 0; bj < 2; ++bj) { const f32x4 v0 = acc[ai][bj][m][0], v1 = acc[ai][bj][m][1]; u32x4 w;
;                     w.x = cvt_pk_bf16((v0[0] * t0[0] - v0[1] * t0[1]) * sc, (v0[0] * t0[1] + v0[1] * t0[0]) * sc);
;                     w.y = cvt_pk_bf16((v0[2] * t0[2] - v0[3] * t0[3]) * sc, (v0[2] * t0[3] + v0[3] * t0[2]) * sc);
;                     w.z = cvt_pk_bf16((v1[0] * t1[0] - v1[1] * t1[1]) * sc, (v1[0] * t1[1] + v1[1] * t1[0]) * sc);
;                     w.w = cvt_pk_bf16((v1[2] * t1[2] - v1[3] * t1[3]) * sc, (v1[2] * t1[3] + v1[3] * t1[2]) * sc);
;                     *(u32x4*)(rowp + bj * HALF) = w; } }
.LBB0_1047:
	v_add_u32_e32 v44, s55, v168
	v_mov_b64_e32 v[42:43], s[44:45]
	v_mad_i64_i32 v[42:43], s[66:67], v44, s79, v[42:43]
	s_waitcnt vmcnt(6)
	v_pk_mul_f32 v[44:45], v[28:29], v[198:199]
	v_pk_mul_f32 v[28:29], v[28:29], v[198:199] op_sel:[0,1] op_sel_hi:[1,0]
	v_sub_f32_e32 v44, v44, v45
	v_add_f32_e32 v28, v28, v29
	v_mul_f32_e32 v44, v188, v44
	v_mul_f32_e32 v28, v188, v28
	v_cvt_pk_bf16_f32 v28, v44, v28
	v_pk_mul_f32 v[44:45], v[30:31], v[200:201]
	v_pk_mul_f32 v[30:31], v[30:31], v[200:201] op_sel:[0,1] op_sel_hi:[1,0]
	v_sub_f32_e32 v29, v44, v45
	v_add_f32_e32 v30, v30, v31
	v_mul_f32_e32 v29, v188, v29
	v_mul_f32_e32 v30, v188, v30
	v_cvt_pk_bf16_f32 v29, v29, v30
	v_pk_mul_f32 v[30:31], v[24:25], v[194:195]
	v_pk_mul_f32 v[24:25], v[24:25], v[194:195] op_sel:[0,1] op_sel_hi:[1,0]
	v_sub_f32_e32 v30, v30, v31
	v_add_f32_e32 v24, v24, v25
	v_mul_f32_e32 v30, v188, v30
	v_mul_f32_e32 v24, v188, v24
	v_cvt_pk_bf16_f32 v30, v30, v24
	v_pk_mul_f32 v[24:25], v[26:27], v[196:197]
	v_lshl_add_u64 v[42:43], v[154:155], 1, v[42:43]
	v_sub_f32_e32 v24, v24, v25
	v_mul_f32_e32 v31, v188, v24
	v_pk_mul_f32 v[24:25], v[26:27], v[196:197] op_sel:[0,1] op_sel_hi:[1,0]
	s_and_b64 vcc, exec, s[10:11]
	v_add_f32_e32 v24, v24, v25
	v_mul_f32_e32 v24, v188, v24
	v_cvt_pk_bf16_f32 v31, v31, v24
	v_pk_mul_f32 v[24:25], v[20:21], v[198:199]
	v_pk_mul_f32 v[20:21], v[20:21], v[198:199] op_sel:[0,1] op_sel_hi:[1,0]
	v_sub_f32_e32 v24, v24, v25
	v_add_f32_e32 v20, v20, v21
	v_mul_f32_e32 v24, v188, v24
	v_mul_f32_e32 v20, v188, v20
	global_store_dwordx4 v[42:43], v[28:31], off
	v_cvt_pk_bf16_f32 v20, v24, v20
	v_pk_mul_f32 v[24:25], v[22:23], v[200:201]
	v_pk_mul_f32 v[22:23], v[22:23], v[200:201] op_sel:[0,1] op_sel_hi:[1,0]
	v_sub_f32_e32 v21, v24, v25
	v_add_f32_e32 v22, v22, v23
	v_mul_f32_e32 v21, v188, v21
	v_mul_f32_e32 v22, v188, v22
	v_cvt_pk_bf16_f32 v21, v21, v22
	v_pk_mul_f32 v[22:23], v[16:17], v[194:195]
	v_pk_mul_f32 v[16:17], v[16:17], v[194:195] op_sel:[0,1] op_sel_hi:[1,0]
	v_sub_f32_e32 v22, v22, v23
	v_add_f32_e32 v16, v16, v17
	v_mul_f32_e32 v22, v188, v22
	v_mul_f32_e32 v16, v188, v16
	v_cvt_pk_bf16_f32 v22, v22, v16
	v_pk_mul_f32 v[16:17], v[18:19], v[196:197]
	v_mov_b32_e32 v34, 1.0
	v_sub_f32_e32 v16, v16, v17
	v_mul_f32_e32 v23, v188, v16
	v_pk_mul_f32 v[16:17], v[18:19], v[196:197] op_sel:[0,1] op_sel_hi:[1,0]
	v_mov_b32_e32 v35, 0
	v_add_f32_e32 v16, v16, v17
	v_mul_f32_e32 v16, v188, v16
	v_cvt_pk_bf16_f32 v23, v23, v16
	v_mov_b32_e32 v16, 1.0
	v_mov_b32_e32 v17, 0
	v_mov_b32_e32 v18, 1.0
	v_mov_b32_e32 v19, 0
	global_store_dwordx4 v[42:43], v[20:23], off offset:256
	s_nop 1
.LBB0_1049:
	s_nop 0
	v_add_u32_e32 v22, s55, v169
	v_mov_b64_e32 v[20:21], s[44:45]
	v_mad_i64_i32 v[20:21], s[10:11], v22, s79, v[20:21]
	s_waitcnt vmcnt(4)
	v_pk_mul_f32 v[22:23], v[12:13], v[206:207]
	v_pk_mul_f32 v[12:13], v[12:13], v[206:207] op_sel:[0,1] op_sel_hi:[1,0]
	v_sub_f32_e32 v22, v22, v23
	v_add_f32_e32 v12, v12, v13
	v_mul_f32_e32 v22, v188, v22
	v_mul_f32_e32 v12, v188, v12
	v_cvt_pk_bf16_f32 v12, v22, v12
	v_pk_mul_f32 v[22:23], v[14:15], v[208:209]
	v_pk_mul_f32 v[14:15], v[14:15], v[208:209] op_sel:[0,1] op_sel_hi:[1,0]
	v_sub_f32_e32 v13, v22, v23
	v_add_f32_e32 v14, v14, v15
	v_mul_f32_e32 v13, v188, v13
	v_mul_f32_e32 v14, v188, v14
	v_cvt_pk_bf16_f32 v13, v13, v14
	v_pk_mul_f32 v[14:15], v[8:9], v[202:203]
	v_pk_mul_f32 v[8:9], v[8:9], v[202:203] op_sel:[0,1] op_sel_hi:[1,0]
	v_sub_f32_e32 v14, v14, v15
	v_add_f32_e32 v8, v8, v9
	v_mul_f32_e32 v14, v188, v14
	v_mul_f32_e32 v8, v188, v8
	v_cvt_pk_bf16_f32 v14, v14, v8
	v_pk_mul_f32 v[8:9], v[10:11], v[204:205]
	v_lshl_add_u64 v[20:21], v[154:155], 1, v[20:21]
	v_sub_f32_e32 v8, v8, v9
	v_mul_f32_e32 v15, v188, v8
	v_pk_mul_f32 v[8:9], v[10:11], v[204:205] op_sel:[0,1] op_sel_hi:[1,0]
	s_andn2_b64 vcc, exec, s[8:9]
	v_add_f32_e32 v8, v8, v9
	v_mul_f32_e32 v8, v188, v8
	v_cvt_pk_bf16_f32 v15, v15, v8
	v_pk_mul_f32 v[8:9], v[4:5], v[206:207]
	v_pk_mul_f32 v[4:5], v[4:5], v[206:207] op_sel:[0,1] op_sel_hi:[1,0]
	v_sub_f32_e32 v8, v8, v9
	v_add_f32_e32 v4, v4, v5
	v_mul_f32_e32 v8, v188, v8
	v_mul_f32_e32 v4, v188, v4
	global_store_dwordx4 v[20:21], v[12:15], off
	v_cvt_pk_bf16_f32 v4, v8, v4
	v_pk_mul_f32 v[8:9], v[6:7], v[208:209]
	v_pk_mul_f32 v[6:7], v[6:7], v[208:209] op_sel:[0,1] op_sel_hi:[1,0]
	v_sub_f32_e32 v5, v8, v9
	v_add_f32_e32 v6, v6, v7
	v_mul_f32_e32 v5, v188, v5
	v_mul_f32_e32 v6, v188, v6
	v_cvt_pk_bf16_f32 v5, v5, v6
	v_pk_mul_f32 v[6:7], v[0:1], v[202:203]
	v_pk_mul_f32 v[0:1], v[0:1], v[202:203] op_sel:[0,1] op_sel_hi:[1,0]
	v_sub_f32_e32 v6, v6, v7
	v_add_f32_e32 v0, v0, v1
	v_mul_f32_e32 v6, v188, v6
	v_mul_f32_e32 v0, v188, v0
	v_cvt_pk_bf16_f32 v6, v6, v0
	v_pk_mul_f32 v[0:1], v[2:3], v[204:205]
	s_mov_b64 s[8:9], -1
	v_sub_f32_e32 v0, v0, v1
	v_mul_f32_e32 v7, v188, v0
	v_pk_mul_f32 v[0:1], v[2:3], v[204:205] op_sel:[0,1] op_sel_hi:[1,0]
	s_nop 0
	v_add_f32_e32 v0, v0, v1
	v_mul_f32_e32 v0, v188, v0
	v_cvt_pk_bf16_f32 v7, v7, v0
	global_store_dwordx4 v[20:21], v[4:7], off offset:256
	s_cbranch_vccnz .LBB0_1026
	s_andn2_b64 vcc, exec, s[36:37]
	s_cbranch_vccnz .LBB0_1025
	s_barrier
	s_branch .LBB0_1025
